# attn64: s_setprio 1/0 flips around QK and PV MFMA sections (stacked on v19)
# baseline (speedup 1.0000x reference)
; template <int DQ>
; __device__ __forceinline__ void attn_unit(LAS unsigned char* lds, const AttnDesc& A, int tid_in, int wid, int lane_in) {
;     ...
;         if (act) {
;             f32x16 s0, s1;
;             bf16x8 kq[2][2];
;             kq[0][0] = *(const LAS bf16x8*)(kb + r32 * KSTR + (8 * h) * 2); kq[0][1] = *(const LAS bf16x8*)(kb + (32 + r32) * KSTR + (8 * h) * 2);
;             __builtin_amdgcn_sched_group_barrier(0x100, 2, 0);
; #pragma unroll
;             for (int s = 0; s < NS; ++s) {
;                 if (s + 1 < NS) {
;                     kq[(s + 1) & 1][0] = *(const LAS bf16x8*)(kb + r32 * KSTR + (16 * (s + 1) + 8 * h) * 2);
;                     kq[(s + 1) & 1][1] = *(const LAS bf16x8*)(kb + (32 + r32) * KSTR + (16 * (s + 1) + 8 * h) * 2);
;                     __builtin_amdgcn_sched_group_barrier(0x100, 2, 0);
;                 }
;                 s0 = __builtin_amdgcn_mfma_f32_32x32x16_bf16(kq[s & 1][0], qf[s], s == 0 ? zero16 : s0, 0, 0, 0);
;                 s1 = __builtin_amdgcn_mfma_f32_32x32x16_bf16(kq[s & 1][1], qf[s], s == 0 ? zero16 : s1, 0, 0, 0);
;                 __builtin_amdgcn_sched_group_barrier(0x008, 2, 0);
;             }
;             if (loc && A.mode == 1) {
;                 const int qc = 32 * (wid & 1) + r32;
;                 const int w0 = min(max(qc - 8, 0), 48);
;                 const int rbase = (A.a0 + t - A.a1 + 7) * 31;
; #pragma unroll
;                 for (int r = 0; r < 16; ++r) {
;                     const int kc = (r & 3) + 8 * (r >> 2) + 4 * h;
;                     { const int dc = min(max(kc - qc + 15, 0), 30); const bool ok = (unsigned)(kc - w0) < 16u; const float bv = rpbl[rbase + dc]; s0[r] = ok ? s0[r] + bv : -1e30f; }
;                     { const int kc2 = kc + 32; const int dc = min(max(kc2 - qc + 15, 0), 30); const bool ok = (unsigned)(kc2 - w0) < 16u; const float bv = rpbl[rbase + dc]; s1[r] = ok ? s1[r] + bv : -1e30f; }
;                 }
;             } else if (loc && A.mode == 2) {
;                 const int p0 = A.a0 + 64 * t;
;                 if (p0 < A.a1 + 31 - 128 || p0 + 63 > A.a1 + 128) {
;                     const int dbase = p0 - (A.a1 + r32);
; #pragma unroll
;                     for (int r = 0; r < 16; ++r) {
;                         const int kc = (r & 3) + 8 * (r >> 2) + 4 * h;
;                         s0[r] = ((unsigned)(dbase + kc + 128) > 256u) ? -1e30f : s0[r];
.LBB0_60:
	s_andn2_b64 vcc, exec, s[52:53]
	s_cbranch_vccnz .LBB0_135
	s_setprio 1
	v_add3_u32 v0, s83, v177, v156
	ds_read_b128 v[2:5], v0
	ds_read_b128 v[6:9], v0 offset:4608
	ds_read_b128 v[10:13], v0 offset:32
	ds_read_b128 v[114:117], v0 offset:4640
	s_andn2_b64 vcc, exec, s[50:51]
	s_mov_b64 s[50:51], -1
	s_waitcnt lgkmcnt(0)
	v_mfma_f32_32x32x16_bf16 v[66:81], v[2:5], v[130:133], v[16:31]
	v_mfma_f32_32x32x16_bf16 v[82:97], v[6:9], v[130:133], v[16:31]
	ds_read_b128 v[2:5], v0 offset:64
	ds_read_b128 v[6:9], v0 offset:4672
	v_mfma_f32_32x32x16_bf16 v[66:81], v[10:13], v[134:137], v[66:81]
	v_mfma_f32_32x32x16_bf16 v[82:97], v[114:117], v[134:137], v[82:97]
	ds_read_b128 v[10:13], v0 offset:96
	ds_read_b128 v[114:117], v0 offset:4704
	s_waitcnt lgkmcnt(0)
	v_mfma_f32_32x32x16_bf16 v[66:81], v[2:5], v[138:141], v[66:81]
	v_mfma_f32_32x32x16_bf16 v[82:97], v[6:9], v[138:141], v[82:97]
	v_mfma_f32_32x32x16_bf16 v[66:81], v[10:13], v[142:145], v[66:81]
	v_mfma_f32_32x32x16_bf16 v[82:97], v[114:117], v[142:145], v[82:97]
	s_setprio 0
	s_cbranch_vccz .LBB0_66
	s_and_b64 s[48:49], s[86:87], s[48:49]
	s_nop 8
	s_andn2_b64 vcc, exec, s[48:49]
	s_cbranch_vccnz .LBB0_65
	s_add_i32 s50, s55, s41
	s_cmp_lt_i32 s50, s63
	s_cselect_b64 s[48:49], -1, 0
	s_cmp_gt_i32 s50, s80
	s_cselect_b64 s[50:51], -1, 0
	s_or_b64 s[48:49], s[48:49], s[50:51]
	s_andn2_b64 vcc, exec, s[48:49]
	s_cbranch_vccnz .LBB0_65
	v_add_u32_e32 v0, s55, v159
	v_add_u32_e32 v2, 0xffffff7f, v0
	s_movk_i32 s48, 0xfefe
	v_cmp_lt_u32_e32 vcc, s48, v2
	v_add_u32_e32 v2, 0xffffff9f, v0
	s_nop 0
	v_cndmask_b32_e32 v66, v241, v66, vcc
	v_cmp_lt_u32_e32 vcc, s48, v2
	v_add_u32_e32 v2, 0xffffff80, v0
	s_nop 0
	v_cndmask_b32_e32 v82, v241, v82, vcc
	v_cmp_lt_u32_e32 vcc, s48, v2
	v_add_u32_e32 v2, 0xffffffa0, v0
	s_nop 0
	v_cndmask_b32_e32 v67, v241, v67, vcc
	v_cmp_lt_u32_e32 vcc, s48, v2
	v_add_u32_e32 v2, 0xffffff81, v0
	s_nop 0
	v_cndmask_b32_e32 v83, v241, v83, vcc
	v_cmp_lt_u32_e32 vcc, s48, v2
	v_add_u32_e32 v2, 0xffffffa1, v0
	s_nop 0
	v_cndmask_b32_e32 v68, v241, v68, vcc
	v_cmp_lt_u32_e32 vcc, s48, v2
	v_add_u32_e32 v2, 0xffffff82, v0
	s_nop 0
	v_cndmask_b32_e32 v84, v241, v84, vcc
	v_cmp_lt_u32_e32 vcc, s48, v2
	v_add_u32_e32 v2, 0xffffffa2, v0
	s_nop 0
	v_cndmask_b32_e32 v69, v241, v69, vcc
	v_cmp_lt_u32_e32 vcc, s48, v2
	v_add_u32_e32 v2, 0xffffff87, v0
	s_nop 0
	v_cndmask_b32_e32 v85, v241, v85, vcc
	v_cmp_lt_u32_e32 vcc, s48, v2
	v_add_u32_e32 v2, 0xffffffa7, v0
	s_nop 0
	v_cndmask_b32_e32 v70, v241, v70, vcc
	v_cmp_lt_u32_e32 vcc, s48, v2
	v_add_u32_e32 v2, 0xffffff88, v0
	s_nop 0
	v_cndmask_b32_e32 v86, v241, v86, vcc
	v_cmp_lt_u32_e32 vcc, s48, v2
	v_add_u32_e32 v2, 0xffffffa8, v0
	s_nop 0
	v_cndmask_b32_e32 v71, v241, v71, vcc
	v_cmp_lt_u32_e32 vcc, s48, v2
	v_add_u32_e32 v2, 0xffffff89, v0
	s_nop 0
	v_cndmask_b32_e32 v87, v241, v87, vcc
	v_cmp_lt_u32_e32 vcc, s48, v2
	v_add_u32_e32 v2, 0xffffffa9, v0
	s_nop 0
	v_cndmask_b32_e32 v72, v241, v72, vcc
	v_cmp_lt_u32_e32 vcc, s48, v2
	v_add_u32_e32 v2, 0xffffff8a, v0
	s_nop 0
	v_cndmask_b32_e32 v88, v241, v88, vcc
	v_cmp_lt_u32_e32 vcc, s48, v2
	v_add_u32_e32 v2, 0xffffffaa, v0
	s_nop 0
	v_cndmask_b32_e32 v73, v241, v73, vcc
	v_cmp_lt_u32_e32 vcc, s48, v2
	v_add_u32_e32 v2, 0xffffff8f, v0
	s_nop 0
	v_cndmask_b32_e32 v89, v241, v89, vcc
	v_cmp_lt_u32_e32 vcc, s48, v2
	v_add_u32_e32 v2, 0xffffffaf, v0
	s_nop 0
	v_cndmask_b32_e32 v74, v241, v74, vcc
	v_cmp_lt_u32_e32 vcc, s48, v2
	v_add_u32_e32 v2, 0xffffff90, v0
	s_nop 0
	v_cndmask_b32_e32 v90, v241, v90, vcc
	v_cmp_lt_u32_e32 vcc, s48, v2
	v_add_u32_e32 v2, 0xffffffb0, v0
	s_nop 0
	v_cndmask_b32_e32 v75, v241, v75, vcc
	v_cmp_lt_u32_e32 vcc, s48, v2
	v_add_u32_e32 v2, 0xffffff91, v0
	s_nop 0
	v_cndmask_b32_e32 v91, v241, v91, vcc
	v_cmp_lt_u32_e32 vcc, s48, v2
	v_add_u32_e32 v2, 0xffffffb1, v0
	s_nop 0
	v_cndmask_b32_e32 v76, v241, v76, vcc
	v_cmp_lt_u32_e32 vcc, s48, v2
	v_add_u32_e32 v2, 0xffffff92, v0
	s_nop 0
	v_cndmask_b32_e32 v92, v241, v92, vcc
	v_cmp_lt_u32_e32 vcc, s48, v2
	v_add_u32_e32 v2, 0xffffffb2, v0
	s_nop 0
	v_cndmask_b32_e32 v77, v241, v77, vcc
	v_cmp_lt_u32_e32 vcc, s48, v2
	v_add_u32_e32 v2, 0xffffff97, v0
	s_nop 0
	v_cndmask_b32_e32 v93, v241, v93, vcc
	v_cmp_lt_u32_e32 vcc, s48, v2
	v_add_u32_e32 v2, 0xffffffb7, v0
	s_nop 0
	v_cndmask_b32_e32 v78, v241, v78, vcc
	v_cmp_lt_u32_e32 vcc, s48, v2
	v_add_u32_e32 v2, 0xffffff98, v0
	s_nop 0
	v_cndmask_b32_e32 v94, v241, v94, vcc
	v_cmp_lt_u32_e32 vcc, s48, v2
	v_add_u32_e32 v2, 0xffffffb8, v0
	s_nop 0
	v_cndmask_b32_e32 v79, v241, v79, vcc
	v_cmp_lt_u32_e32 vcc, s48, v2
	v_add_u32_e32 v2, 0xffffff99, v0
	s_nop 0
	v_cndmask_b32_e32 v95, v241, v95, vcc
	v_cmp_lt_u32_e32 vcc, s48, v2
	v_add_u32_e32 v2, 0xffffffb9, v0
	s_nop 0
	v_cndmask_b32_e32 v80, v241, v80, vcc
	v_cmp_lt_u32_e32 vcc, s48, v2
	v_add_u32_e32 v2, 0xffffff9a, v0
	v_add_u32_e32 v0, 0xffffffba, v0
	v_cndmask_b32_e32 v96, v241, v96, vcc
	v_cmp_lt_u32_e32 vcc, s48, v2
	s_nop 1
	v_cndmask_b32_e32 v81, v241, v81, vcc
	v_cmp_lt_u32_e32 vcc, s48, v0
	s_nop 1
	v_cndmask_b32_e32 v97, v241, v97, vcc

; __device__ __forceinline__ unsigned cvt_pk_bf16_m(float lo, float hi) { const f32x2_cv v = {lo, hi}; const bf16x2_cv b = __builtin_convertvector(v, bf16x2_cv); return __builtin_bit_cast(unsigned, b); }
; template <int DQ>
; __device__ __forceinline__ void attn_unit(LAS unsigned char* lds, const AttnDesc& A, int tid_in, int wid, int lane_in) {
;     ...
;             float rsa = 0.f, rsb = 0.f;
; #pragma unroll
;             for (int r = 0; r < 16; ++r) { s0[r] = __builtin_amdgcn_exp2f(s0[r] - mrun); s1[r] = __builtin_amdgcn_exp2f(s1[r] - mrun); rsa += s0[r]; rsb += s1[r]; }
;             lrun += rsa + rsb;
;             bf16x8 pf[4];
; #pragma unroll
;             for (int s2 = 0; s2 < 2; ++s2) {
;                 u32x4 w;
;                 w.x = cvt_pk_bf16_m(s0[8 * s2 + 0], s0[8 * s2 + 1]); w.y = cvt_pk_bf16_m(s0[8 * s2 + 2], s0[8 * s2 + 3]); w.z = cvt_pk_bf16_m(s0[8 * s2 + 4], s0[8 * s2 + 5]); w.w = cvt_pk_bf16_m(s0[8 * s2 + 6], s0[8 * s2 + 7]);
;                 pf[s2] = __builtin_bit_cast(bf16x8, w);
;                 w.x = cvt_pk_bf16_m(s1[8 * s2 + 0], s1[8 * s2 + 1]); w.y = cvt_pk_bf16_m(s1[8 * s2 + 2], s1[8 * s2 + 3]); w.z = cvt_pk_bf16_m(s1[8 * s2 + 4], s1[8 * s2 + 5]); w.w = cvt_pk_bf16_m(s1[8 * s2 + 6], s1[8 * s2 + 7]);
;                 pf[2 + s2] = __builtin_bit_cast(bf16x8, w);
;             }
;             bf16x8 vq[2][2];
;     ...
;             ATT_VRD(0, 0);
; #pragma unroll
;             for (int ks = 0; ks < 4; ++ks) {
;                 if (ks + 1 < 4) ATT_VRD((ks + 1) & 1, ks + 1);
;                 o0 = __builtin_amdgcn_mfma_f32_32x32x16_bf16(vq[ks & 1][0], pf[ks], o0, 0, 0, 0);
;                 o1 = __builtin_amdgcn_mfma_f32_32x32x16_bf16(vq[ks & 1][1], pf[ks], o1, 0, 0, 0);
;             }
.LBB0_134:
	v_exp_f32_e32 v3, v66
	v_exp_f32_e32 v2, v82
	v_exp_f32_e32 v5, v67
	v_exp_f32_e32 v4, v83
	v_exp_f32_e32 v9, v68
	v_exp_f32_e32 v8, v84
	v_exp_f32_e32 v11, v69
	v_exp_f32_e32 v10, v85
	v_exp_f32_e32 v15, v70
	v_exp_f32_e32 v14, v86
	v_exp_f32_e32 v71, v71
	v_exp_f32_e32 v70, v87
	v_exp_f32_e32 v83, v72
	v_exp_f32_e32 v82, v88
	v_exp_f32_e32 v73, v73
	v_exp_f32_e32 v72, v89
	v_exp_f32_e32 v85, v74
	v_exp_f32_e32 v84, v90
	v_exp_f32_e32 v75, v75
	v_exp_f32_e32 v74, v91
	v_exp_f32_e32 v87, v76
	v_cvt_pk_bf16_f32 v66, v3, v5
	v_cvt_pk_bf16_f32 v6, v2, v4
	v_pk_add_f32 v[2:3], v[2:3], 0 op_sel_hi:[1,0]
	v_exp_f32_e32 v86, v92
	v_pk_add_f32 v[2:3], v[4:5], v[2:3]
	v_exp_f32_e32 v77, v77
	v_pk_add_f32 v[2:3], v[8:9], v[2:3]
	v_exp_f32_e32 v76, v93
	v_pk_add_f32 v[92:93], v[10:11], v[2:3]
	v_exp_f32_e32 v89, v78
	v_cvt_pk_bf16_f32 v7, v8, v10
	v_cvt_pk_bf16_f32 v68, v15, v71
	v_cvt_pk_bf16_f32 v8, v14, v70
	v_pk_add_f32 v[14:15], v[14:15], v[92:93]
	v_exp_f32_e32 v88, v94
	v_pk_add_f32 v[14:15], v[70:71], v[14:15]
	v_exp_f32_e32 v79, v79
	v_pk_add_f32 v[14:15], v[82:83], v[14:15]
	v_exp_f32_e32 v78, v95
	v_pk_add_f32 v[14:15], v[72:73], v[14:15]
	v_exp_f32_e32 v91, v80
	v_pk_add_f32 v[14:15], v[84:85], v[14:15]
	v_exp_f32_e32 v90, v96
	v_pk_add_f32 v[14:15], v[74:75], v[14:15]
	v_exp_f32_e32 v81, v81
	v_pk_add_f32 v[14:15], v[86:87], v[14:15]
	v_exp_f32_e32 v80, v97
	v_pk_add_f32 v[14:15], v[76:77], v[14:15]
	v_cvt_pk_bf16_f32 v67, v9, v11
	v_pk_add_f32 v[14:15], v[88:89], v[14:15]
	v_cvt_pk_bf16_f32 v69, v83, v73
	v_pk_add_f32 v[14:15], v[78:79], v[14:15]
	v_cvt_pk_bf16_f32 v9, v82, v72
	v_pk_add_f32 v[14:15], v[90:91], v[14:15]
	v_cvt_pk_bf16_f32 v10, v85, v75
	v_pk_add_f32 v[14:15], v[80:81], v[14:15]
	v_cvt_pk_bf16_f32 v11, v87, v77
	v_add_f32_e32 v0, v14, v15
	v_add_u32_e32 v14, s18, v65
	v_add3_u32 v14, v14, v171, v172
	v_cvt_pk_bf16_f32 v12, v89, v79
	v_cvt_pk_bf16_f32 v13, v91, v81
	v_cvt_pk_bf16_f32 v2, v84, v74
	v_cvt_pk_bf16_f32 v3, v86, v76
	v_cvt_pk_bf16_f32 v4, v88, v78
	v_cvt_pk_bf16_f32 v5, v90, v80
	s_setprio 1
	ds_read_b64_tr_b16 v[70:71], v14 offset:26624
	ds_read_b64_tr_b16 v[72:73], v14 offset:27136
	ds_read_b64_tr_b16 v[74:75], v14 offset:30720
	ds_read_b64_tr_b16 v[76:77], v14 offset:31232
	ds_read_b64_tr_b16 v[78:79], v14 offset:27648
	ds_read_b64_tr_b16 v[80:81], v14 offset:28160
	ds_read_b64_tr_b16 v[82:83], v14 offset:31744
	ds_read_b64_tr_b16 v[84:85], v14 offset:32256
	s_waitcnt lgkmcnt(0)
	v_mfma_f32_32x32x16_bf16 v[48:63], v[70:73], v[66:69], v[48:63]
	v_add_f32_e32 v64, v64, v0
	v_mfma_f32_32x32x16_bf16 v[32:47], v[74:77], v[66:69], v[32:47]
	ds_read_b64_tr_b16 v[66:67], v14 offset:28672
	ds_read_b64_tr_b16 v[68:69], v14 offset:29184
	ds_read_b64_tr_b16 v[70:71], v14 offset:32768
	ds_read_b64_tr_b16 v[72:73], v14 offset:33280
	v_mfma_f32_32x32x16_bf16 v[48:63], v[78:81], v[10:13], v[48:63]
	v_mfma_f32_32x32x16_bf16 v[32:47], v[82:85], v[10:13], v[32:47]
	ds_read_b64_tr_b16 v[10:11], v14 offset:29696
	ds_read_b64_tr_b16 v[12:13], v14 offset:30208
	ds_read_b64_tr_b16 v[74:75], v14 offset:33792
	ds_read_b64_tr_b16 v[76:77], v14 offset:34304
	s_waitcnt lgkmcnt(0)
	v_mfma_f32_32x32x16_bf16 v[48:63], v[66:69], v[6:9], v[48:63]
	v_mfma_f32_32x32x16_bf16 v[32:47], v[70:73], v[6:9], v[32:47]
	v_mfma_f32_32x32x16_bf16 v[48:63], v[10:13], v[2:5], v[48:63]
	v_mfma_f32_32x32x16_bf16 v[32:47], v[74:77], v[2:5], v[32:47]
	s_setprio 0
